# 7.12 ballot trim in the top-k compaction: 8 v_cndmask + 12 v_cmp_ne re-deriving masks already in SGPRs replaced by s_mov_b64
# baseline (speedup 1.0000x reference)
; __device__ __forceinline__ void phase_cmp(const Params& p, LAS unsigned char* lds, const bf16_t* Z, const float* G, const bf16_t* KC, const bf16_t* ACCW, float* ACC, int* IDX, ...
;     ...
;                 int n_gt = 0;
; #pragma unroll
;                 for (int i = 0; i < 4; ++i) n_gt += __builtin_popcountll(__ballot(ok[i] && v[i] > T));
;                 int* dst = IDX + (((size_t)b * SEQ + qb * 64 + qi) * 2 + g) * 16;
;                 if (lane == 0) { dst[0] = 0; dst[1] = cur - 1; dst[2] = cur; }
;                 int pos_gt = 3, eq_seen = 0; const int eq_base = 3 + n_gt, need = 13 - n_gt;
; #pragma unroll
;                 for (int i = 0; i < 4; ++i) {
;                     const bool gt = ok[i] && v[i] > T, eq = ok[i] && v[i] == T;
;                     const unsigned long long mg = __ballot(gt), me = __ballot(eq);
;                     const int rg = __builtin_amdgcn_mbcnt_hi((unsigned)(mg >> 32), __builtin_amdgcn_mbcnt_lo((unsigned)mg, 0u));
;                     const int re = __builtin_amdgcn_mbcnt_hi((unsigned)(me >> 32), __builtin_amdgcn_mbcnt_lo((unsigned)me, 0u));
;                     if (gt) dst[pos_gt + rg] = lane + 64 * i;
.Ltk_join:
	s_mov_b32 s22, -1
	v_cmp_lt_u32_e64 s[20:21], s96, v2
	s_and_b64 s[80:81], s[70:71], s[20:21]
	v_cmp_lt_u32_e64 s[20:21], s96, v5
	s_and_b64 s[78:79], vcc, s[20:21]
	v_cmp_lt_u32_e64 s[20:21], s96, v4
	s_and_b64 s[76:77], s[16:17], s[20:21]
	v_cmp_lt_u32_e64 s[20:21], s96, v0
	s_and_b64 s[74:75], s[18:19], s[20:21]
	s_ashr_i32 s21, s95, 31
	s_add_u32 s20, s95, s26
	s_addc_u32 s21, s21, 0
	s_lshl_b64 s[20:21], s[20:21], 7
	s_add_u32 s72, s92, s20
	s_mov_b64 s[22:23], s[80:81]
	s_mov_b64 s[24:25], s[78:79]
	s_mov_b64 s[38:39], s[76:77]
	s_mov_b64 s[40:41], s[74:75]
	s_addc_u32 s73, s93, s21
	s_and_saveexec_b64 s[20:21], s[8:9]
	s_cbranch_execz .LBB0_436
	v_mov_b32_e32 v11, s94
	v_mov_b32_e32 v12, s91
	v_mov_b32_e32 v10, v1
	global_store_dwordx3 v1, v[10:12], s[72:73]
.LBB0_436:
	s_or_b64 exec, exec, s[20:21]
	v_cmp_eq_u32_e64 s[20:21], s96, v2
	s_and_b64 s[82:83], s[70:71], s[20:21]
	s_mov_b64 s[42:43], s[80:81]
	s_mov_b64 s[20:21], s[82:83]
	s_and_saveexec_b64 s[84:85], s[80:81]
	s_cbranch_execz .LBB0_438
	v_mbcnt_lo_u32_b32 v2, s42, 0
	v_mbcnt_hi_u32_b32 v2, s43, v2
	v_lshlrev_b32_e32 v2, 2, v2
	global_store_dword v2, v77, s[72:73] offset:12

; __device__ __forceinline__ void phase_cmp(const Params& p, LAS unsigned char* lds, const bf16_t* Z, const float* G, const bf16_t* KC, const bf16_t* ACCW, float* ACC, int* IDX, ...
;     ...
; #pragma unroll
;                 for (int i = 0; i < 4; ++i) {
;                     const bool gt = ok[i] && v[i] > T, eq = ok[i] && v[i] == T;
;                     const unsigned long long mg = __ballot(gt), me = __ballot(eq);
;                     const int rg = __builtin_amdgcn_mbcnt_hi((unsigned)(mg >> 32), __builtin_amdgcn_mbcnt_lo((unsigned)mg, 0u));
;                     const int re = __builtin_amdgcn_mbcnt_hi((unsigned)(me >> 32), __builtin_amdgcn_mbcnt_lo((unsigned)me, 0u));
;                     if (gt) dst[pos_gt + rg] = lane + 64 * i;
;                     if (eq && eq_seen + re < need) dst[eq_base + eq_seen + re] = lane + 64 * i;
;                     pos_gt += __builtin_popcountll(mg); eq_seen += __builtin_popcountll(me);
;                 }
.LBB0_440:
	s_or_b64 exec, exec, s[22:23]
	s_cmp_lt_u32 s91, 66
	s_cbranch_scc1 .LBB0_423
	v_cmp_eq_u32_e64 s[22:23], s96, v5
	s_and_b64 s[38:39], vcc, s[22:23]
	s_bcnt1_i32_b64 s81, s[42:43]
	s_mov_b64 s[24:25], s[78:79]
	s_mov_b64 s[22:23], s[38:39]
	s_and_saveexec_b64 s[42:43], s[78:79]
	s_cbranch_execz .LBB0_442
	v_mbcnt_lo_u32_b32 v2, s24, 0
	v_mbcnt_hi_u32_b32 v2, s25, v2
	v_add_lshl_u32 v2, v2, s81, 2
	global_store_dword v2, v127, s[72:73] offset:12

; __device__ __forceinline__ void phase_cmp(const Params& p, LAS unsigned char* lds, const bf16_t* Z, const float* G, const bf16_t* KC, const bf16_t* ACCW, float* ACC, int* IDX, ...
;     ...
; #pragma unroll
;                 for (int i = 0; i < 4; ++i) {
;                     const bool gt = ok[i] && v[i] > T, eq = ok[i] && v[i] == T;
;                     const unsigned long long mg = __ballot(gt), me = __ballot(eq);
;                     const int rg = __builtin_amdgcn_mbcnt_hi((unsigned)(mg >> 32), __builtin_amdgcn_mbcnt_lo((unsigned)mg, 0u));
;                     const int re = __builtin_amdgcn_mbcnt_hi((unsigned)(me >> 32), __builtin_amdgcn_mbcnt_lo((unsigned)me, 0u));
;                     if (gt) dst[pos_gt + rg] = lane + 64 * i;
;                     if (eq && eq_seen + re < need) dst[eq_base + eq_seen + re] = lane + 64 * i;
;                     pos_gt += __builtin_popcountll(mg); eq_seen += __builtin_popcountll(me);
;                 }
.LBB0_444:
	s_or_b64 exec, exec, s[20:21]
	s_cmpk_lt_u32 s91, 0x82
	s_cbranch_scc1 .LBB0_423
	v_cmp_eq_u32_e64 s[20:21], s96, v4
	s_and_b64 s[38:39], s[16:17], s[20:21]
	s_bcnt1_i32_b64 s78, s[24:25]
	s_mov_b64 s[24:25], s[76:77]
	s_mov_b64 s[20:21], s[38:39]
	s_and_saveexec_b64 s[42:43], s[76:77]
	s_cbranch_execz .LBB0_446
	v_mbcnt_lo_u32_b32 v2, s24, 0
	v_mbcnt_hi_u32_b32 v2, s25, v2
	s_add_i32 s41, s81, s78
	v_add_lshl_u32 v2, v2, s41, 2
	global_store_dword v2, v129, s[72:73] offset:12

; __device__ __forceinline__ void phase_cmp(const Params& p, LAS unsigned char* lds, const bf16_t* Z, const float* G, const bf16_t* KC, const bf16_t* ACCW, float* ACC, int* IDX, ...
;     ...
; #pragma unroll
;                 for (int i = 0; i < 4; ++i) {
;                     const bool gt = ok[i] && v[i] > T, eq = ok[i] && v[i] == T;
;                     const unsigned long long mg = __ballot(gt), me = __ballot(eq);
;                     const int rg = __builtin_amdgcn_mbcnt_hi((unsigned)(mg >> 32), __builtin_amdgcn_mbcnt_lo((unsigned)mg, 0u));
;                     const int re = __builtin_amdgcn_mbcnt_hi((unsigned)(me >> 32), __builtin_amdgcn_mbcnt_lo((unsigned)me, 0u));
;                     if (gt) dst[pos_gt + rg] = lane + 64 * i;
;                     if (eq && eq_seen + re < need) dst[eq_base + eq_seen + re] = lane + 64 * i;
;                     pos_gt += __builtin_popcountll(mg); eq_seen += __builtin_popcountll(me);
;                 }
.LBB0_448:
	s_or_b64 exec, exec, s[22:23]
	v_cmp_eq_u32_e64 s[22:23], s96, v0
	s_and_b64 s[42:43], s[18:19], s[22:23]
	s_mov_b64 s[38:39], s[74:75]
	s_mov_b64 s[22:23], s[42:43]
	s_and_saveexec_b64 s[76:77], s[74:75]
	s_cbranch_execz .LBB0_450
	s_bcnt1_i32_b64 s24, s[24:25]
	v_mbcnt_lo_u32_b32 v0, s38, 0
	s_add_i32 s25, s81, s78
	v_mbcnt_hi_u32_b32 v0, s39, v0
	s_add_i32 s25, s25, s24
	v_add_lshl_u32 v0, s25, v0, 2
	global_store_dword v0, v131, s[72:73] offset:12
